# prune bisection counts entries per trial bin on byte-packed bin indices (sub + and + bcnt per four entries) instead of compare + add-with-carry per entry
# speedup vs baseline: 1.0144x; 1.0144x over previous
.Lp2apr0_iter:
	v_sub_u32_e32 v38, v35, v34
	v_or_b32_e32 v41, 1, v38
	v_ffbh_u32_e32 v41, v41
	v_sub_u32_e32 v41, 26, v41
	v_max_i32_e32 v39, 0, v41
	v_mov_b32_e32 v36, 0
	v_sub_u32_e64 v56, v0, v34 clamp
	v_lshrrev_b32_e32 v56, v39, v56
	v_min_u32_e32 v48, 0x7f, v56
	v_sub_u32_e64 v56, v1, v34 clamp
	v_lshrrev_b32_e32 v56, v39, v56
	v_min_u32_e32 v56, 0x7f, v56
	v_lshl_or_b32 v48, v56, 8, v48
	v_sub_u32_e64 v56, v2, v34 clamp
	v_lshrrev_b32_e32 v56, v39, v56
	v_min_u32_e32 v56, 0x7f, v56
	v_lshl_or_b32 v48, v56, 16, v48
	v_sub_u32_e64 v56, v3, v34 clamp
	v_lshrrev_b32_e32 v56, v39, v56
	v_min_u32_e32 v56, 0x7f, v56
	v_lshl_or_b32 v48, v56, 24, v48
	v_sub_u32_e64 v56, v4, v34 clamp
	v_lshrrev_b32_e32 v56, v39, v56
	v_min_u32_e32 v49, 0x7f, v56
	v_sub_u32_e64 v56, v5, v34 clamp
	v_lshrrev_b32_e32 v56, v39, v56
	v_min_u32_e32 v56, 0x7f, v56
	v_lshl_or_b32 v49, v56, 8, v49
	v_sub_u32_e64 v56, v6, v34 clamp
	v_lshrrev_b32_e32 v56, v39, v56
	v_min_u32_e32 v56, 0x7f, v56
	v_lshl_or_b32 v49, v56, 16, v49
	v_sub_u32_e64 v56, v7, v34 clamp
	v_lshrrev_b32_e32 v56, v39, v56
	v_min_u32_e32 v56, 0x7f, v56
	v_lshl_or_b32 v49, v56, 24, v49
	v_sub_u32_e64 v56, v8, v34 clamp
	v_lshrrev_b32_e32 v56, v39, v56
	v_min_u32_e32 v50, 0x7f, v56
	v_sub_u32_e64 v56, v9, v34 clamp
	v_lshrrev_b32_e32 v56, v39, v56
	v_min_u32_e32 v56, 0x7f, v56
	v_lshl_or_b32 v50, v56, 8, v50
	v_sub_u32_e64 v56, v10, v34 clamp
	v_lshrrev_b32_e32 v56, v39, v56
	v_min_u32_e32 v56, 0x7f, v56
	v_lshl_or_b32 v50, v56, 16, v50
	v_sub_u32_e64 v56, v11, v34 clamp
	v_lshrrev_b32_e32 v56, v39, v56
	v_min_u32_e32 v56, 0x7f, v56
	v_lshl_or_b32 v50, v56, 24, v50
	v_sub_u32_e64 v56, v12, v34 clamp
	v_lshrrev_b32_e32 v56, v39, v56
	v_min_u32_e32 v51, 0x7f, v56
	v_sub_u32_e64 v56, v13, v34 clamp
	v_lshrrev_b32_e32 v56, v39, v56
	v_min_u32_e32 v56, 0x7f, v56
	v_lshl_or_b32 v51, v56, 8, v51
	v_sub_u32_e64 v56, v14, v34 clamp
	v_lshrrev_b32_e32 v56, v39, v56
	v_min_u32_e32 v56, 0x7f, v56
	v_lshl_or_b32 v51, v56, 16, v51
	v_sub_u32_e64 v56, v15, v34 clamp
	v_lshrrev_b32_e32 v56, v39, v56
	v_min_u32_e32 v56, 0x7f, v56
	v_lshl_or_b32 v51, v56, 24, v51
	v_sub_u32_e64 v56, v16, v34 clamp
	v_lshrrev_b32_e32 v56, v39, v56
	v_min_u32_e32 v52, 0x7f, v56
	v_sub_u32_e64 v56, v17, v34 clamp
	v_lshrrev_b32_e32 v56, v39, v56
	v_min_u32_e32 v56, 0x7f, v56
	v_lshl_or_b32 v52, v56, 8, v52
	v_sub_u32_e64 v56, v18, v34 clamp
	v_lshrrev_b32_e32 v56, v39, v56
	v_min_u32_e32 v56, 0x7f, v56
	v_lshl_or_b32 v52, v56, 16, v52
	v_sub_u32_e64 v56, v19, v34 clamp
	v_lshrrev_b32_e32 v56, v39, v56
	v_min_u32_e32 v56, 0x7f, v56
	v_lshl_or_b32 v52, v56, 24, v52
	v_sub_u32_e64 v56, v20, v34 clamp
	v_lshrrev_b32_e32 v56, v39, v56
	v_min_u32_e32 v53, 0x7f, v56
	v_sub_u32_e64 v56, v21, v34 clamp
	v_lshrrev_b32_e32 v56, v39, v56
	v_min_u32_e32 v56, 0x7f, v56
	v_lshl_or_b32 v53, v56, 8, v53
	v_sub_u32_e64 v56, v22, v34 clamp
	v_lshrrev_b32_e32 v56, v39, v56
	v_min_u32_e32 v56, 0x7f, v56
	v_lshl_or_b32 v53, v56, 16, v53
	v_sub_u32_e64 v56, v23, v34 clamp
	v_lshrrev_b32_e32 v56, v39, v56
	v_min_u32_e32 v56, 0x7f, v56
	v_lshl_or_b32 v53, v56, 24, v53
	v_sub_u32_e64 v56, v24, v34 clamp
	v_lshrrev_b32_e32 v56, v39, v56
	v_min_u32_e32 v54, 0x7f, v56
	v_sub_u32_e64 v56, v25, v34 clamp
	v_lshrrev_b32_e32 v56, v39, v56
	v_min_u32_e32 v56, 0x7f, v56
	v_lshl_or_b32 v54, v56, 8, v54
	v_sub_u32_e64 v56, v26, v34 clamp
	v_lshrrev_b32_e32 v56, v39, v56
	v_min_u32_e32 v56, 0x7f, v56
	v_lshl_or_b32 v54, v56, 16, v54
	v_sub_u32_e64 v56, v27, v34 clamp
	v_lshrrev_b32_e32 v56, v39, v56
	v_min_u32_e32 v56, 0x7f, v56
	v_lshl_or_b32 v54, v56, 24, v54
	v_sub_u32_e64 v56, v28, v34 clamp
	v_lshrrev_b32_e32 v56, v39, v56
	v_min_u32_e32 v55, 0x7f, v56
	v_sub_u32_e64 v56, v29, v34 clamp
	v_lshrrev_b32_e32 v56, v39, v56
	v_min_u32_e32 v56, 0x7f, v56
	v_lshl_or_b32 v55, v56, 8, v55
	v_sub_u32_e64 v56, v30, v34 clamp
	v_lshrrev_b32_e32 v56, v39, v56
	v_min_u32_e32 v56, 0x7f, v56
	v_lshl_or_b32 v55, v56, 16, v55
	v_sub_u32_e64 v56, v31, v34 clamp
	v_lshrrev_b32_e32 v56, v39, v56
	v_min_u32_e32 v56, 0x7f, v56
	v_lshl_or_b32 v55, v56, 24, v55
	v_or_b32_e32 v42, 0x20202020, v36
	v_subrev_u32_e32 v43, 0x80808080, v42
	v_mov_b32_e32 v44, 0
	v_sub_u32_e32 v41, v48, v43
	v_and_b32_e32 v41, 0x80808080, v41
	v_bcnt_u32_b32 v44, v41, v44
	v_sub_u32_e32 v45, v49, v43
	v_and_b32_e32 v45, 0x80808080, v45
	v_bcnt_u32_b32 v44, v45, v44
	v_sub_u32_e32 v41, v50, v43
	v_and_b32_e32 v41, 0x80808080, v41
	v_bcnt_u32_b32 v44, v41, v44
	v_sub_u32_e32 v45, v51, v43
	v_and_b32_e32 v45, 0x80808080, v45
	v_bcnt_u32_b32 v44, v45, v44
	v_sub_u32_e32 v41, v52, v43
	v_and_b32_e32 v41, 0x80808080, v41
	v_bcnt_u32_b32 v44, v41, v44
	v_sub_u32_e32 v45, v53, v43
	v_and_b32_e32 v45, 0x80808080, v45
	v_bcnt_u32_b32 v44, v45, v44
	v_sub_u32_e32 v41, v54, v43
	v_and_b32_e32 v41, 0x80808080, v41
	v_bcnt_u32_b32 v44, v41, v44
	v_sub_u32_e32 v45, v55, v43
	v_and_b32_e32 v45, 0x80808080, v45
	v_bcnt_u32_b32 v44, v45, v44
	v_mov_b32_e32 v45, v44
	s_nop 1
	v_add_u32_dpp v45, v45, v45 row_ror:1 row_mask:0xf bank_mask:0xf
	s_nop 1
	v_add_u32_dpp v45, v45, v45 row_ror:2 row_mask:0xf bank_mask:0xf
	s_nop 1
	v_add_u32_dpp v45, v45, v45 row_ror:4 row_mask:0xf bank_mask:0xf
	s_nop 1
	v_add_u32_dpp v45, v45, v45 row_ror:8 row_mask:0xf bank_mask:0xf
	s_nop 0
	v_cmp_le_u32_e32 vcc, 0x100, v45
	s_nop 1
	v_cndmask_b32_e32 v36, v36, v42, vcc
	v_cndmask_b32_e32 v46, v46, v45, vcc
	v_cndmask_b32_e32 v47, v47, v44, vcc
	v_or_b32_e32 v42, 0x10101010, v36
	v_subrev_u32_e32 v43, 0x80808080, v42
	v_mov_b32_e32 v44, 0
	v_sub_u32_e32 v41, v48, v43
	v_and_b32_e32 v41, 0x80808080, v41
	v_bcnt_u32_b32 v44, v41, v44
	v_sub_u32_e32 v45, v49, v43
	v_and_b32_e32 v45, 0x80808080, v45
	v_bcnt_u32_b32 v44, v45, v44
	v_sub_u32_e32 v41, v50, v43
	v_and_b32_e32 v41, 0x80808080, v41
	v_bcnt_u32_b32 v44, v41, v44
	v_sub_u32_e32 v45, v51, v43
	v_and_b32_e32 v45, 0x80808080, v45
	v_bcnt_u32_b32 v44, v45, v44
	v_sub_u32_e32 v41, v52, v43
	v_and_b32_e32 v41, 0x80808080, v41
	v_bcnt_u32_b32 v44, v41, v44
	v_sub_u32_e32 v45, v53, v43
	v_and_b32_e32 v45, 0x80808080, v45
	v_bcnt_u32_b32 v44, v45, v44
	v_sub_u32_e32 v41, v54, v43
	v_and_b32_e32 v41, 0x80808080, v41
	v_bcnt_u32_b32 v44, v41, v44
	v_sub_u32_e32 v45, v55, v43
	v_and_b32_e32 v45, 0x80808080, v45
	v_bcnt_u32_b32 v44, v45, v44
	v_mov_b32_e32 v45, v44
	s_nop 1
	v_add_u32_dpp v45, v45, v45 row_ror:1 row_mask:0xf bank_mask:0xf
	s_nop 1
	v_add_u32_dpp v45, v45, v45 row_ror:2 row_mask:0xf bank_mask:0xf
	s_nop 1
	v_add_u32_dpp v45, v45, v45 row_ror:4 row_mask:0xf bank_mask:0xf
	s_nop 1
	v_add_u32_dpp v45, v45, v45 row_ror:8 row_mask:0xf bank_mask:0xf
	s_nop 0
	v_cmp_le_u32_e32 vcc, 0x100, v45
	s_nop 1
	v_cndmask_b32_e32 v36, v36, v42, vcc
	v_cndmask_b32_e32 v46, v46, v45, vcc
	v_cndmask_b32_e32 v47, v47, v44, vcc
	v_or_b32_e32 v42, 0x8080808, v36
	v_subrev_u32_e32 v43, 0x80808080, v42
	v_mov_b32_e32 v44, 0
	v_sub_u32_e32 v41, v48, v43
	v_and_b32_e32 v41, 0x80808080, v41
	v_bcnt_u32_b32 v44, v41, v44
	v_sub_u32_e32 v45, v49, v43
	v_and_b32_e32 v45, 0x80808080, v45
	v_bcnt_u32_b32 v44, v45, v44
	v_sub_u32_e32 v41, v50, v43
	v_and_b32_e32 v41, 0x80808080, v41
	v_bcnt_u32_b32 v44, v41, v44
	v_sub_u32_e32 v45, v51, v43
	v_and_b32_e32 v45, 0x80808080, v45
	v_bcnt_u32_b32 v44, v45, v44
	v_sub_u32_e32 v41, v52, v43
	v_and_b32_e32 v41, 0x80808080, v41
	v_bcnt_u32_b32 v44, v41, v44
	v_sub_u32_e32 v45, v53, v43
	v_and_b32_e32 v45, 0x80808080, v45
	v_bcnt_u32_b32 v44, v45, v44
	v_sub_u32_e32 v41, v54, v43
	v_and_b32_e32 v41, 0x80808080, v41
	v_bcnt_u32_b32 v44, v41, v44
	v_sub_u32_e32 v45, v55, v43
	v_and_b32_e32 v45, 0x80808080, v45
	v_bcnt_u32_b32 v44, v45, v44
	v_mov_b32_e32 v45, v44
	s_nop 1
	v_add_u32_dpp v45, v45, v45 row_ror:1 row_mask:0xf bank_mask:0xf
	s_nop 1
	v_add_u32_dpp v45, v45, v45 row_ror:2 row_mask:0xf bank_mask:0xf
	s_nop 1
	v_add_u32_dpp v45, v45, v45 row_ror:4 row_mask:0xf bank_mask:0xf
	s_nop 1
	v_add_u32_dpp v45, v45, v45 row_ror:8 row_mask:0xf bank_mask:0xf
	s_nop 0
	v_cmp_le_u32_e32 vcc, 0x100, v45
	s_nop 1
	v_cndmask_b32_e32 v36, v36, v42, vcc
	v_cndmask_b32_e32 v46, v46, v45, vcc
	v_cndmask_b32_e32 v47, v47, v44, vcc
	v_or_b32_e32 v42, 0x4040404, v36
	v_subrev_u32_e32 v43, 0x80808080, v42
	v_mov_b32_e32 v44, 0
	v_sub_u32_e32 v41, v48, v43
	v_and_b32_e32 v41, 0x80808080, v41
	v_bcnt_u32_b32 v44, v41, v44
	v_sub_u32_e32 v45, v49, v43
	v_and_b32_e32 v45, 0x80808080, v45
	v_bcnt_u32_b32 v44, v45, v44
	v_sub_u32_e32 v41, v50, v43
	v_and_b32_e32 v41, 0x80808080, v41
	v_bcnt_u32_b32 v44, v41, v44
	v_sub_u32_e32 v45, v51, v43
	v_and_b32_e32 v45, 0x80808080, v45
	v_bcnt_u32_b32 v44, v45, v44
	v_sub_u32_e32 v41, v52, v43
	v_and_b32_e32 v41, 0x80808080, v41
	v_bcnt_u32_b32 v44, v41, v44
	v_sub_u32_e32 v45, v53, v43
	v_and_b32_e32 v45, 0x80808080, v45
	v_bcnt_u32_b32 v44, v45, v44
	v_sub_u32_e32 v41, v54, v43
	v_and_b32_e32 v41, 0x80808080, v41
	v_bcnt_u32_b32 v44, v41, v44
	v_sub_u32_e32 v45, v55, v43
	v_and_b32_e32 v45, 0x80808080, v45
	v_bcnt_u32_b32 v44, v45, v44
	v_mov_b32_e32 v45, v44
	s_nop 1
	v_add_u32_dpp v45, v45, v45 row_ror:1 row_mask:0xf bank_mask:0xf
	s_nop 1
	v_add_u32_dpp v45, v45, v45 row_ror:2 row_mask:0xf bank_mask:0xf
	s_nop 1
	v_add_u32_dpp v45, v45, v45 row_ror:4 row_mask:0xf bank_mask:0xf
	s_nop 1
	v_add_u32_dpp v45, v45, v45 row_ror:8 row_mask:0xf bank_mask:0xf
	s_nop 0
	v_cmp_le_u32_e32 vcc, 0x100, v45
	s_nop 1
	v_cndmask_b32_e32 v36, v36, v42, vcc
	v_cndmask_b32_e32 v46, v46, v45, vcc
	v_cndmask_b32_e32 v47, v47, v44, vcc
	v_or_b32_e32 v42, 0x2020202, v36
	v_subrev_u32_e32 v43, 0x80808080, v42
	v_mov_b32_e32 v44, 0
	v_sub_u32_e32 v41, v48, v43
	v_and_b32_e32 v41, 0x80808080, v41
	v_bcnt_u32_b32 v44, v41, v44
	v_sub_u32_e32 v45, v49, v43
	v_and_b32_e32 v45, 0x80808080, v45
	v_bcnt_u32_b32 v44, v45, v44
	v_sub_u32_e32 v41, v50, v43
	v_and_b32_e32 v41, 0x80808080, v41
	v_bcnt_u32_b32 v44, v41, v44
	v_sub_u32_e32 v45, v51, v43
	v_and_b32_e32 v45, 0x80808080, v45
	v_bcnt_u32_b32 v44, v45, v44
	v_sub_u32_e32 v41, v52, v43
	v_and_b32_e32 v41, 0x80808080, v41
	v_bcnt_u32_b32 v44, v41, v44
	v_sub_u32_e32 v45, v53, v43
	v_and_b32_e32 v45, 0x80808080, v45
	v_bcnt_u32_b32 v44, v45, v44
	v_sub_u32_e32 v41, v54, v43
	v_and_b32_e32 v41, 0x80808080, v41
	v_bcnt_u32_b32 v44, v41, v44
	v_sub_u32_e32 v45, v55, v43
	v_and_b32_e32 v45, 0x80808080, v45
	v_bcnt_u32_b32 v44, v45, v44
	v_mov_b32_e32 v45, v44
	s_nop 1
	v_add_u32_dpp v45, v45, v45 row_ror:1 row_mask:0xf bank_mask:0xf
	s_nop 1
	v_add_u32_dpp v45, v45, v45 row_ror:2 row_mask:0xf bank_mask:0xf
	s_nop 1
	v_add_u32_dpp v45, v45, v45 row_ror:4 row_mask:0xf bank_mask:0xf
	s_nop 1
	v_add_u32_dpp v45, v45, v45 row_ror:8 row_mask:0xf bank_mask:0xf
	s_nop 0
	v_cmp_le_u32_e32 vcc, 0x100, v45
	s_nop 1
	v_cndmask_b32_e32 v36, v36, v42, vcc
	v_cndmask_b32_e32 v46, v46, v45, vcc
	v_cndmask_b32_e32 v47, v47, v44, vcc
	v_or_b32_e32 v42, 0x1010101, v36
	v_subrev_u32_e32 v43, 0x80808080, v42
	v_mov_b32_e32 v44, 0
	v_sub_u32_e32 v41, v48, v43
	v_and_b32_e32 v41, 0x80808080, v41
	v_bcnt_u32_b32 v44, v41, v44
	v_sub_u32_e32 v45, v49, v43
	v_and_b32_e32 v45, 0x80808080, v45
	v_bcnt_u32_b32 v44, v45, v44
	v_sub_u32_e32 v41, v50, v43
	v_and_b32_e32 v41, 0x80808080, v41
	v_bcnt_u32_b32 v44, v41, v44
	v_sub_u32_e32 v45, v51, v43
	v_and_b32_e32 v45, 0x80808080, v45
	v_bcnt_u32_b32 v44, v45, v44
	v_sub_u32_e32 v41, v52, v43
	v_and_b32_e32 v41, 0x80808080, v41
	v_bcnt_u32_b32 v44, v41, v44
	v_sub_u32_e32 v45, v53, v43
	v_and_b32_e32 v45, 0x80808080, v45
	v_bcnt_u32_b32 v44, v45, v44
	v_sub_u32_e32 v41, v54, v43
	v_and_b32_e32 v41, 0x80808080, v41
	v_bcnt_u32_b32 v44, v41, v44
	v_sub_u32_e32 v45, v55, v43
	v_and_b32_e32 v45, 0x80808080, v45
	v_bcnt_u32_b32 v44, v45, v44
	v_mov_b32_e32 v45, v44
	s_nop 1
	v_add_u32_dpp v45, v45, v45 row_ror:1 row_mask:0xf bank_mask:0xf
	s_nop 1
	v_add_u32_dpp v45, v45, v45 row_ror:2 row_mask:0xf bank_mask:0xf
	s_nop 1
	v_add_u32_dpp v45, v45, v45 row_ror:4 row_mask:0xf bank_mask:0xf
	s_nop 1
	v_add_u32_dpp v45, v45, v45 row_ror:8 row_mask:0xf bank_mask:0xf
	s_nop 0
	v_cmp_le_u32_e32 vcc, 0x100, v45
	s_nop 1
	v_cndmask_b32_e32 v36, v36, v42, vcc
	v_cndmask_b32_e32 v46, v46, v45, vcc
	v_cndmask_b32_e32 v47, v47, v44, vcc
	v_and_b32_e32 v41, 0x7f, v36
	v_lshlrev_b32_e32 v41, v39, v41
	v_add_u32_e32 v41, v34, v41
	v_cmp_ge_u32_e32 vcc, 0x120, v46
	v_cmp_eq_u32_e64 s[0:1], 0, v39
	v_lshlrev_b32_e32 v42, v39, v200
	v_add_u32_e32 v42, -1, v42
	s_or_b64 vcc, vcc, s[0:1]
	s_andn2_b64 s[0:1], vcc, s[50:51]
	s_nor_b64 s[2:3], vcc, s[50:51]
	s_or_b64 s[50:51], s[50:51], vcc
	v_add_u32_e64 v42, v41, v42 clamp
	v_min_u32_e32 v42, v42, v35
	v_cndmask_b32_e64 v37, v37, v41, s[0:1]
	v_cndmask_b32_e64 v62, v62, v47, s[0:1]
	v_cndmask_b32_e64 v35, v35, v42, s[2:3]
	v_cndmask_b32_e64 v34, v34, v41, s[2:3]
	s_cmp_eq_u64 s[50:51], -1
	s_cbranch_scc0 .Lp2apr0_iter
	s_mov_b64 exec, s[22:23]
	v_mov_b32_e32 v61, v62
	s_nop 1
	v_add_u32_dpp v61, v61, v61 row_shr:1 row_mask:0xf bank_mask:0xf bound_ctrl:1
	s_nop 1
	v_add_u32_dpp v61, v61, v61 row_shr:2 row_mask:0xf bank_mask:0xf bound_ctrl:1
	s_nop 1
	v_add_u32_dpp v61, v61, v61 row_shr:4 row_mask:0xf bank_mask:0xf bound_ctrl:1
	s_nop 1
	v_add_u32_dpp v61, v61, v61 row_shr:8 row_mask:0xf bank_mask:0xf bound_ctrl:1
	v_sub_u32_e32 v62, v61, v62
	v_lshl_add_u32 v41, v62, 2, v59
	v_cmpx_ge_u32_e32 vcc, v0, v37
	v_add_u32_e32 v62, 1, v62
	ds_write_b32 v41, v0
	s_mov_b64 exec, s[22:23]
	v_lshl_add_u32 v41, v62, 2, v59
	v_cmpx_ge_u32_e32 vcc, v1, v37
	v_add_u32_e32 v62, 1, v62
	ds_write_b32 v41, v1
	s_mov_b64 exec, s[22:23]
	v_lshl_add_u32 v41, v62, 2, v59
	v_cmpx_ge_u32_e32 vcc, v2, v37
	v_add_u32_e32 v62, 1, v62
	ds_write_b32 v41, v2
	s_mov_b64 exec, s[22:23]
	v_lshl_add_u32 v41, v62, 2, v59
	v_cmpx_ge_u32_e32 vcc, v3, v37
	v_add_u32_e32 v62, 1, v62
	ds_write_b32 v41, v3
	s_mov_b64 exec, s[22:23]
	v_lshl_add_u32 v41, v62, 2, v59
	v_cmpx_ge_u32_e32 vcc, v4, v37
	v_add_u32_e32 v62, 1, v62
	ds_write_b32 v41, v4
	s_mov_b64 exec, s[22:23]
	v_lshl_add_u32 v41, v62, 2, v59
	v_cmpx_ge_u32_e32 vcc, v5, v37
	v_add_u32_e32 v62, 1, v62
	ds_write_b32 v41, v5
	s_mov_b64 exec, s[22:23]
	v_lshl_add_u32 v41, v62, 2, v59
	v_cmpx_ge_u32_e32 vcc, v6, v37
	v_add_u32_e32 v62, 1, v62
	ds_write_b32 v41, v6
	s_mov_b64 exec, s[22:23]
	v_lshl_add_u32 v41, v62, 2, v59
	v_cmpx_ge_u32_e32 vcc, v7, v37
	v_add_u32_e32 v62, 1, v62
	ds_write_b32 v41, v7
	s_mov_b64 exec, s[22:23]
	v_lshl_add_u32 v41, v62, 2, v59
	v_cmpx_ge_u32_e32 vcc, v8, v37
	v_add_u32_e32 v62, 1, v62
	ds_write_b32 v41, v8
	s_mov_b64 exec, s[22:23]
	v_lshl_add_u32 v41, v62, 2, v59
	v_cmpx_ge_u32_e32 vcc, v9, v37
	v_add_u32_e32 v62, 1, v62
	ds_write_b32 v41, v9
	s_mov_b64 exec, s[22:23]
	v_lshl_add_u32 v41, v62, 2, v59
	v_cmpx_ge_u32_e32 vcc, v10, v37
	v_add_u32_e32 v62, 1, v62
	ds_write_b32 v41, v10
	s_mov_b64 exec, s[22:23]
	v_lshl_add_u32 v41, v62, 2, v59
	v_cmpx_ge_u32_e32 vcc, v11, v37
	v_add_u32_e32 v62, 1, v62
	ds_write_b32 v41, v11
	s_mov_b64 exec, s[22:23]
	v_lshl_add_u32 v41, v62, 2, v59
	v_cmpx_ge_u32_e32 vcc, v12, v37
	v_add_u32_e32 v62, 1, v62
	ds_write_b32 v41, v12
	s_mov_b64 exec, s[22:23]
	v_lshl_add_u32 v41, v62, 2, v59
	v_cmpx_ge_u32_e32 vcc, v13, v37
	v_add_u32_e32 v62, 1, v62
	ds_write_b32 v41, v13
	s_mov_b64 exec, s[22:23]
	v_lshl_add_u32 v41, v62, 2, v59
	v_cmpx_ge_u32_e32 vcc, v14, v37
	v_add_u32_e32 v62, 1, v62
	ds_write_b32 v41, v14
	s_mov_b64 exec, s[22:23]
	v_lshl_add_u32 v41, v62, 2, v59
	v_cmpx_ge_u32_e32 vcc, v15, v37
	v_add_u32_e32 v62, 1, v62
	ds_write_b32 v41, v15
	s_mov_b64 exec, s[22:23]
	v_lshl_add_u32 v41, v62, 2, v59
	v_cmpx_ge_u32_e32 vcc, v16, v37
	v_add_u32_e32 v62, 1, v62
	ds_write_b32 v41, v16
	s_mov_b64 exec, s[22:23]
	v_lshl_add_u32 v41, v62, 2, v59
	v_cmpx_ge_u32_e32 vcc, v17, v37
	v_add_u32_e32 v62, 1, v62
	ds_write_b32 v41, v17
	s_mov_b64 exec, s[22:23]
	v_lshl_add_u32 v41, v62, 2, v59
	v_cmpx_ge_u32_e32 vcc, v18, v37
	v_add_u32_e32 v62, 1, v62
	ds_write_b32 v41, v18
	s_mov_b64 exec, s[22:23]
	v_lshl_add_u32 v41, v62, 2, v59
	v_cmpx_ge_u32_e32 vcc, v19, v37
	v_add_u32_e32 v62, 1, v62
	ds_write_b32 v41, v19
	s_mov_b64 exec, s[22:23]
	v_lshl_add_u32 v41, v62, 2, v59
	v_cmpx_ge_u32_e32 vcc, v20, v37
	v_add_u32_e32 v62, 1, v62
	ds_write_b32 v41, v20
	s_mov_b64 exec, s[22:23]
	v_lshl_add_u32 v41, v62, 2, v59
	v_cmpx_ge_u32_e32 vcc, v21, v37
	v_add_u32_e32 v62, 1, v62
	ds_write_b32 v41, v21
	s_mov_b64 exec, s[22:23]
	v_lshl_add_u32 v41, v62, 2, v59
	v_cmpx_ge_u32_e32 vcc, v22, v37
	v_add_u32_e32 v62, 1, v62
	ds_write_b32 v41, v22
	s_mov_b64 exec, s[22:23]
	v_lshl_add_u32 v41, v62, 2, v59
	v_cmpx_ge_u32_e32 vcc, v23, v37
	v_add_u32_e32 v62, 1, v62
	ds_write_b32 v41, v23
	s_mov_b64 exec, s[22:23]
	v_lshl_add_u32 v41, v62, 2, v59
	v_cmpx_ge_u32_e32 vcc, v24, v37
	v_add_u32_e32 v62, 1, v62
	ds_write_b32 v41, v24
	s_mov_b64 exec, s[22:23]
	v_lshl_add_u32 v41, v62, 2, v59
	v_cmpx_ge_u32_e32 vcc, v25, v37
	v_add_u32_e32 v62, 1, v62
	ds_write_b32 v41, v25
	s_mov_b64 exec, s[22:23]
	v_lshl_add_u32 v41, v62, 2, v59
	v_cmpx_ge_u32_e32 vcc, v26, v37
	v_add_u32_e32 v62, 1, v62
	ds_write_b32 v41, v26
	s_mov_b64 exec, s[22:23]
	v_lshl_add_u32 v41, v62, 2, v59
	v_cmpx_ge_u32_e32 vcc, v27, v37
	v_add_u32_e32 v62, 1, v62
	ds_write_b32 v41, v27
	s_mov_b64 exec, s[22:23]
	v_lshl_add_u32 v41, v62, 2, v59
	v_cmpx_ge_u32_e32 vcc, v28, v37
	v_add_u32_e32 v62, 1, v62
	ds_write_b32 v41, v28
	s_mov_b64 exec, s[22:23]
	v_lshl_add_u32 v41, v62, 2, v59
	v_cmpx_ge_u32_e32 vcc, v29, v37
	v_add_u32_e32 v62, 1, v62
	ds_write_b32 v41, v29
	s_mov_b64 exec, s[22:23]
	v_lshl_add_u32 v41, v62, 2, v59
	v_cmpx_ge_u32_e32 vcc, v30, v37
	v_add_u32_e32 v62, 1, v62
	ds_write_b32 v41, v30
	s_mov_b64 exec, s[22:23]
	v_lshl_add_u32 v41, v62, 2, v59
	v_cmpx_ge_u32_e32 vcc, v31, v37
	v_add_u32_e32 v62, 1, v62
	ds_write_b32 v41, v31
	s_mov_b64 exec, s[22:23]
	s_mov_b64 exec, -1
	v_and_b32_e32 v41, 0xffffe000, v37
	v_ashrrev_i32_e32 v42, 31, v41
	v_not_b32_e32 v42, v42
	v_or_b32_e32 v42, 0x80000000, v42
	v_xor_b32_e32 v63, v41, v42
	s_cmpk_lt_i32 s78, 0x121
	s_cbranch_scc1 .Lp2apr0_o0
	v_readlane_b32 s0, v63, 0
	v_readlane_b32 s73, v37, 0
	v_readlane_b32 s78, v61, 15
	v_mov_b32_e32 v231, s0

.Lp2apr1_iter:
	v_sub_u32_e32 v38, v35, v34
	v_or_b32_e32 v41, 1, v38
	v_ffbh_u32_e32 v41, v41
	v_sub_u32_e32 v41, 26, v41
	v_max_i32_e32 v39, 0, v41
	v_mov_b32_e32 v36, 0
	v_sub_u32_e64 v56, v0, v34 clamp
	v_lshrrev_b32_e32 v56, v39, v56
	v_min_u32_e32 v48, 0x7f, v56
	v_sub_u32_e64 v56, v1, v34 clamp
	v_lshrrev_b32_e32 v56, v39, v56
	v_min_u32_e32 v56, 0x7f, v56
	v_lshl_or_b32 v48, v56, 8, v48
	v_sub_u32_e64 v56, v2, v34 clamp
	v_lshrrev_b32_e32 v56, v39, v56
	v_min_u32_e32 v56, 0x7f, v56
	v_lshl_or_b32 v48, v56, 16, v48
	v_sub_u32_e64 v56, v3, v34 clamp
	v_lshrrev_b32_e32 v56, v39, v56
	v_min_u32_e32 v56, 0x7f, v56
	v_lshl_or_b32 v48, v56, 24, v48
	v_sub_u32_e64 v56, v4, v34 clamp
	v_lshrrev_b32_e32 v56, v39, v56
	v_min_u32_e32 v49, 0x7f, v56
	v_sub_u32_e64 v56, v5, v34 clamp
	v_lshrrev_b32_e32 v56, v39, v56
	v_min_u32_e32 v56, 0x7f, v56
	v_lshl_or_b32 v49, v56, 8, v49
	v_sub_u32_e64 v56, v6, v34 clamp
	v_lshrrev_b32_e32 v56, v39, v56
	v_min_u32_e32 v56, 0x7f, v56
	v_lshl_or_b32 v49, v56, 16, v49
	v_sub_u32_e64 v56, v7, v34 clamp
	v_lshrrev_b32_e32 v56, v39, v56
	v_min_u32_e32 v56, 0x7f, v56
	v_lshl_or_b32 v49, v56, 24, v49
	v_sub_u32_e64 v56, v8, v34 clamp
	v_lshrrev_b32_e32 v56, v39, v56
	v_min_u32_e32 v50, 0x7f, v56
	v_sub_u32_e64 v56, v9, v34 clamp
	v_lshrrev_b32_e32 v56, v39, v56
	v_min_u32_e32 v56, 0x7f, v56
	v_lshl_or_b32 v50, v56, 8, v50
	v_sub_u32_e64 v56, v10, v34 clamp
	v_lshrrev_b32_e32 v56, v39, v56
	v_min_u32_e32 v56, 0x7f, v56
	v_lshl_or_b32 v50, v56, 16, v50
	v_sub_u32_e64 v56, v11, v34 clamp
	v_lshrrev_b32_e32 v56, v39, v56
	v_min_u32_e32 v56, 0x7f, v56
	v_lshl_or_b32 v50, v56, 24, v50
	v_sub_u32_e64 v56, v12, v34 clamp
	v_lshrrev_b32_e32 v56, v39, v56
	v_min_u32_e32 v51, 0x7f, v56
	v_sub_u32_e64 v56, v13, v34 clamp
	v_lshrrev_b32_e32 v56, v39, v56
	v_min_u32_e32 v56, 0x7f, v56
	v_lshl_or_b32 v51, v56, 8, v51
	v_sub_u32_e64 v56, v14, v34 clamp
	v_lshrrev_b32_e32 v56, v39, v56
	v_min_u32_e32 v56, 0x7f, v56
	v_lshl_or_b32 v51, v56, 16, v51
	v_sub_u32_e64 v56, v15, v34 clamp
	v_lshrrev_b32_e32 v56, v39, v56
	v_min_u32_e32 v56, 0x7f, v56
	v_lshl_or_b32 v51, v56, 24, v51
	v_sub_u32_e64 v56, v16, v34 clamp
	v_lshrrev_b32_e32 v56, v39, v56
	v_min_u32_e32 v52, 0x7f, v56
	v_sub_u32_e64 v56, v17, v34 clamp
	v_lshrrev_b32_e32 v56, v39, v56
	v_min_u32_e32 v56, 0x7f, v56
	v_lshl_or_b32 v52, v56, 8, v52
	v_sub_u32_e64 v56, v18, v34 clamp
	v_lshrrev_b32_e32 v56, v39, v56
	v_min_u32_e32 v56, 0x7f, v56
	v_lshl_or_b32 v52, v56, 16, v52
	v_sub_u32_e64 v56, v19, v34 clamp
	v_lshrrev_b32_e32 v56, v39, v56
	v_min_u32_e32 v56, 0x7f, v56
	v_lshl_or_b32 v52, v56, 24, v52
	v_sub_u32_e64 v56, v20, v34 clamp
	v_lshrrev_b32_e32 v56, v39, v56
	v_min_u32_e32 v53, 0x7f, v56
	v_sub_u32_e64 v56, v21, v34 clamp
	v_lshrrev_b32_e32 v56, v39, v56
	v_min_u32_e32 v56, 0x7f, v56
	v_lshl_or_b32 v53, v56, 8, v53
	v_sub_u32_e64 v56, v22, v34 clamp
	v_lshrrev_b32_e32 v56, v39, v56
	v_min_u32_e32 v56, 0x7f, v56
	v_lshl_or_b32 v53, v56, 16, v53
	v_sub_u32_e64 v56, v23, v34 clamp
	v_lshrrev_b32_e32 v56, v39, v56
	v_min_u32_e32 v56, 0x7f, v56
	v_lshl_or_b32 v53, v56, 24, v53
	v_sub_u32_e64 v56, v24, v34 clamp
	v_lshrrev_b32_e32 v56, v39, v56
	v_min_u32_e32 v54, 0x7f, v56
	v_sub_u32_e64 v56, v25, v34 clamp
	v_lshrrev_b32_e32 v56, v39, v56
	v_min_u32_e32 v56, 0x7f, v56
	v_lshl_or_b32 v54, v56, 8, v54
	v_sub_u32_e64 v56, v26, v34 clamp
	v_lshrrev_b32_e32 v56, v39, v56
	v_min_u32_e32 v56, 0x7f, v56
	v_lshl_or_b32 v54, v56, 16, v54
	v_sub_u32_e64 v56, v27, v34 clamp
	v_lshrrev_b32_e32 v56, v39, v56
	v_min_u32_e32 v56, 0x7f, v56
	v_lshl_or_b32 v54, v56, 24, v54
	v_sub_u32_e64 v56, v28, v34 clamp
	v_lshrrev_b32_e32 v56, v39, v56
	v_min_u32_e32 v55, 0x7f, v56
	v_sub_u32_e64 v56, v29, v34 clamp
	v_lshrrev_b32_e32 v56, v39, v56
	v_min_u32_e32 v56, 0x7f, v56
	v_lshl_or_b32 v55, v56, 8, v55
	v_sub_u32_e64 v56, v30, v34 clamp
	v_lshrrev_b32_e32 v56, v39, v56
	v_min_u32_e32 v56, 0x7f, v56
	v_lshl_or_b32 v55, v56, 16, v55
	v_sub_u32_e64 v56, v31, v34 clamp
	v_lshrrev_b32_e32 v56, v39, v56
	v_min_u32_e32 v56, 0x7f, v56
	v_lshl_or_b32 v55, v56, 24, v55
	v_or_b32_e32 v42, 0x20202020, v36
	v_subrev_u32_e32 v43, 0x80808080, v42
	v_mov_b32_e32 v44, 0
	v_sub_u32_e32 v41, v48, v43
	v_and_b32_e32 v41, 0x80808080, v41
	v_bcnt_u32_b32 v44, v41, v44
	v_sub_u32_e32 v45, v49, v43
	v_and_b32_e32 v45, 0x80808080, v45
	v_bcnt_u32_b32 v44, v45, v44
	v_sub_u32_e32 v41, v50, v43
	v_and_b32_e32 v41, 0x80808080, v41
	v_bcnt_u32_b32 v44, v41, v44
	v_sub_u32_e32 v45, v51, v43
	v_and_b32_e32 v45, 0x80808080, v45
	v_bcnt_u32_b32 v44, v45, v44
	v_sub_u32_e32 v41, v52, v43
	v_and_b32_e32 v41, 0x80808080, v41
	v_bcnt_u32_b32 v44, v41, v44
	v_sub_u32_e32 v45, v53, v43
	v_and_b32_e32 v45, 0x80808080, v45
	v_bcnt_u32_b32 v44, v45, v44
	v_sub_u32_e32 v41, v54, v43
	v_and_b32_e32 v41, 0x80808080, v41
	v_bcnt_u32_b32 v44, v41, v44
	v_sub_u32_e32 v45, v55, v43
	v_and_b32_e32 v45, 0x80808080, v45
	v_bcnt_u32_b32 v44, v45, v44
	v_mov_b32_e32 v45, v44
	s_nop 1
	v_add_u32_dpp v45, v45, v45 row_ror:1 row_mask:0xf bank_mask:0xf
	s_nop 1
	v_add_u32_dpp v45, v45, v45 row_ror:2 row_mask:0xf bank_mask:0xf
	s_nop 1
	v_add_u32_dpp v45, v45, v45 row_ror:4 row_mask:0xf bank_mask:0xf
	s_nop 1
	v_add_u32_dpp v45, v45, v45 row_ror:8 row_mask:0xf bank_mask:0xf
	s_nop 0
	v_cmp_le_u32_e32 vcc, 0x100, v45
	s_nop 1
	v_cndmask_b32_e32 v36, v36, v42, vcc
	v_cndmask_b32_e32 v46, v46, v45, vcc
	v_cndmask_b32_e32 v47, v47, v44, vcc
	v_or_b32_e32 v42, 0x10101010, v36
	v_subrev_u32_e32 v43, 0x80808080, v42
	v_mov_b32_e32 v44, 0
	v_sub_u32_e32 v41, v48, v43
	v_and_b32_e32 v41, 0x80808080, v41
	v_bcnt_u32_b32 v44, v41, v44
	v_sub_u32_e32 v45, v49, v43
	v_and_b32_e32 v45, 0x80808080, v45
	v_bcnt_u32_b32 v44, v45, v44
	v_sub_u32_e32 v41, v50, v43
	v_and_b32_e32 v41, 0x80808080, v41
	v_bcnt_u32_b32 v44, v41, v44
	v_sub_u32_e32 v45, v51, v43
	v_and_b32_e32 v45, 0x80808080, v45
	v_bcnt_u32_b32 v44, v45, v44
	v_sub_u32_e32 v41, v52, v43
	v_and_b32_e32 v41, 0x80808080, v41
	v_bcnt_u32_b32 v44, v41, v44
	v_sub_u32_e32 v45, v53, v43
	v_and_b32_e32 v45, 0x80808080, v45
	v_bcnt_u32_b32 v44, v45, v44
	v_sub_u32_e32 v41, v54, v43
	v_and_b32_e32 v41, 0x80808080, v41
	v_bcnt_u32_b32 v44, v41, v44
	v_sub_u32_e32 v45, v55, v43
	v_and_b32_e32 v45, 0x80808080, v45
	v_bcnt_u32_b32 v44, v45, v44
	v_mov_b32_e32 v45, v44
	s_nop 1
	v_add_u32_dpp v45, v45, v45 row_ror:1 row_mask:0xf bank_mask:0xf
	s_nop 1
	v_add_u32_dpp v45, v45, v45 row_ror:2 row_mask:0xf bank_mask:0xf
	s_nop 1
	v_add_u32_dpp v45, v45, v45 row_ror:4 row_mask:0xf bank_mask:0xf
	s_nop 1
	v_add_u32_dpp v45, v45, v45 row_ror:8 row_mask:0xf bank_mask:0xf
	s_nop 0
	v_cmp_le_u32_e32 vcc, 0x100, v45
	s_nop 1
	v_cndmask_b32_e32 v36, v36, v42, vcc
	v_cndmask_b32_e32 v46, v46, v45, vcc
	v_cndmask_b32_e32 v47, v47, v44, vcc
	v_or_b32_e32 v42, 0x8080808, v36
	v_subrev_u32_e32 v43, 0x80808080, v42
	v_mov_b32_e32 v44, 0
	v_sub_u32_e32 v41, v48, v43
	v_and_b32_e32 v41, 0x80808080, v41
	v_bcnt_u32_b32 v44, v41, v44
	v_sub_u32_e32 v45, v49, v43
	v_and_b32_e32 v45, 0x80808080, v45
	v_bcnt_u32_b32 v44, v45, v44
	v_sub_u32_e32 v41, v50, v43
	v_and_b32_e32 v41, 0x80808080, v41
	v_bcnt_u32_b32 v44, v41, v44
	v_sub_u32_e32 v45, v51, v43
	v_and_b32_e32 v45, 0x80808080, v45
	v_bcnt_u32_b32 v44, v45, v44
	v_sub_u32_e32 v41, v52, v43
	v_and_b32_e32 v41, 0x80808080, v41
	v_bcnt_u32_b32 v44, v41, v44
	v_sub_u32_e32 v45, v53, v43
	v_and_b32_e32 v45, 0x80808080, v45
	v_bcnt_u32_b32 v44, v45, v44
	v_sub_u32_e32 v41, v54, v43
	v_and_b32_e32 v41, 0x80808080, v41
	v_bcnt_u32_b32 v44, v41, v44
	v_sub_u32_e32 v45, v55, v43
	v_and_b32_e32 v45, 0x80808080, v45
	v_bcnt_u32_b32 v44, v45, v44
	v_mov_b32_e32 v45, v44
	s_nop 1
	v_add_u32_dpp v45, v45, v45 row_ror:1 row_mask:0xf bank_mask:0xf
	s_nop 1
	v_add_u32_dpp v45, v45, v45 row_ror:2 row_mask:0xf bank_mask:0xf
	s_nop 1
	v_add_u32_dpp v45, v45, v45 row_ror:4 row_mask:0xf bank_mask:0xf
	s_nop 1
	v_add_u32_dpp v45, v45, v45 row_ror:8 row_mask:0xf bank_mask:0xf
	s_nop 0
	v_cmp_le_u32_e32 vcc, 0x100, v45
	s_nop 1
	v_cndmask_b32_e32 v36, v36, v42, vcc
	v_cndmask_b32_e32 v46, v46, v45, vcc
	v_cndmask_b32_e32 v47, v47, v44, vcc
	v_or_b32_e32 v42, 0x4040404, v36
	v_subrev_u32_e32 v43, 0x80808080, v42
	v_mov_b32_e32 v44, 0
	v_sub_u32_e32 v41, v48, v43
	v_and_b32_e32 v41, 0x80808080, v41
	v_bcnt_u32_b32 v44, v41, v44
	v_sub_u32_e32 v45, v49, v43
	v_and_b32_e32 v45, 0x80808080, v45
	v_bcnt_u32_b32 v44, v45, v44
	v_sub_u32_e32 v41, v50, v43
	v_and_b32_e32 v41, 0x80808080, v41
	v_bcnt_u32_b32 v44, v41, v44
	v_sub_u32_e32 v45, v51, v43
	v_and_b32_e32 v45, 0x80808080, v45
	v_bcnt_u32_b32 v44, v45, v44
	v_sub_u32_e32 v41, v52, v43
	v_and_b32_e32 v41, 0x80808080, v41
	v_bcnt_u32_b32 v44, v41, v44
	v_sub_u32_e32 v45, v53, v43
	v_and_b32_e32 v45, 0x80808080, v45
	v_bcnt_u32_b32 v44, v45, v44
	v_sub_u32_e32 v41, v54, v43
	v_and_b32_e32 v41, 0x80808080, v41
	v_bcnt_u32_b32 v44, v41, v44
	v_sub_u32_e32 v45, v55, v43
	v_and_b32_e32 v45, 0x80808080, v45
	v_bcnt_u32_b32 v44, v45, v44
	v_mov_b32_e32 v45, v44
	s_nop 1
	v_add_u32_dpp v45, v45, v45 row_ror:1 row_mask:0xf bank_mask:0xf
	s_nop 1
	v_add_u32_dpp v45, v45, v45 row_ror:2 row_mask:0xf bank_mask:0xf
	s_nop 1
	v_add_u32_dpp v45, v45, v45 row_ror:4 row_mask:0xf bank_mask:0xf
	s_nop 1
	v_add_u32_dpp v45, v45, v45 row_ror:8 row_mask:0xf bank_mask:0xf
	s_nop 0
	v_cmp_le_u32_e32 vcc, 0x100, v45
	s_nop 1
	v_cndmask_b32_e32 v36, v36, v42, vcc
	v_cndmask_b32_e32 v46, v46, v45, vcc
	v_cndmask_b32_e32 v47, v47, v44, vcc
	v_or_b32_e32 v42, 0x2020202, v36
	v_subrev_u32_e32 v43, 0x80808080, v42
	v_mov_b32_e32 v44, 0
	v_sub_u32_e32 v41, v48, v43
	v_and_b32_e32 v41, 0x80808080, v41
	v_bcnt_u32_b32 v44, v41, v44
	v_sub_u32_e32 v45, v49, v43
	v_and_b32_e32 v45, 0x80808080, v45
	v_bcnt_u32_b32 v44, v45, v44
	v_sub_u32_e32 v41, v50, v43
	v_and_b32_e32 v41, 0x80808080, v41
	v_bcnt_u32_b32 v44, v41, v44
	v_sub_u32_e32 v45, v51, v43
	v_and_b32_e32 v45, 0x80808080, v45
	v_bcnt_u32_b32 v44, v45, v44
	v_sub_u32_e32 v41, v52, v43
	v_and_b32_e32 v41, 0x80808080, v41
	v_bcnt_u32_b32 v44, v41, v44
	v_sub_u32_e32 v45, v53, v43
	v_and_b32_e32 v45, 0x80808080, v45
	v_bcnt_u32_b32 v44, v45, v44
	v_sub_u32_e32 v41, v54, v43
	v_and_b32_e32 v41, 0x80808080, v41
	v_bcnt_u32_b32 v44, v41, v44
	v_sub_u32_e32 v45, v55, v43
	v_and_b32_e32 v45, 0x80808080, v45
	v_bcnt_u32_b32 v44, v45, v44
	v_mov_b32_e32 v45, v44
	s_nop 1
	v_add_u32_dpp v45, v45, v45 row_ror:1 row_mask:0xf bank_mask:0xf
	s_nop 1
	v_add_u32_dpp v45, v45, v45 row_ror:2 row_mask:0xf bank_mask:0xf
	s_nop 1
	v_add_u32_dpp v45, v45, v45 row_ror:4 row_mask:0xf bank_mask:0xf
	s_nop 1
	v_add_u32_dpp v45, v45, v45 row_ror:8 row_mask:0xf bank_mask:0xf
	s_nop 0
	v_cmp_le_u32_e32 vcc, 0x100, v45
	s_nop 1
	v_cndmask_b32_e32 v36, v36, v42, vcc
	v_cndmask_b32_e32 v46, v46, v45, vcc
	v_cndmask_b32_e32 v47, v47, v44, vcc
	v_or_b32_e32 v42, 0x1010101, v36
	v_subrev_u32_e32 v43, 0x80808080, v42
	v_mov_b32_e32 v44, 0
	v_sub_u32_e32 v41, v48, v43
	v_and_b32_e32 v41, 0x80808080, v41
	v_bcnt_u32_b32 v44, v41, v44
	v_sub_u32_e32 v45, v49, v43
	v_and_b32_e32 v45, 0x80808080, v45
	v_bcnt_u32_b32 v44, v45, v44
	v_sub_u32_e32 v41, v50, v43
	v_and_b32_e32 v41, 0x80808080, v41
	v_bcnt_u32_b32 v44, v41, v44
	v_sub_u32_e32 v45, v51, v43
	v_and_b32_e32 v45, 0x80808080, v45
	v_bcnt_u32_b32 v44, v45, v44
	v_sub_u32_e32 v41, v52, v43
	v_and_b32_e32 v41, 0x80808080, v41
	v_bcnt_u32_b32 v44, v41, v44
	v_sub_u32_e32 v45, v53, v43
	v_and_b32_e32 v45, 0x80808080, v45
	v_bcnt_u32_b32 v44, v45, v44
	v_sub_u32_e32 v41, v54, v43
	v_and_b32_e32 v41, 0x80808080, v41
	v_bcnt_u32_b32 v44, v41, v44
	v_sub_u32_e32 v45, v55, v43
	v_and_b32_e32 v45, 0x80808080, v45
	v_bcnt_u32_b32 v44, v45, v44
	v_mov_b32_e32 v45, v44
	s_nop 1
	v_add_u32_dpp v45, v45, v45 row_ror:1 row_mask:0xf bank_mask:0xf
	s_nop 1
	v_add_u32_dpp v45, v45, v45 row_ror:2 row_mask:0xf bank_mask:0xf
	s_nop 1
	v_add_u32_dpp v45, v45, v45 row_ror:4 row_mask:0xf bank_mask:0xf
	s_nop 1
	v_add_u32_dpp v45, v45, v45 row_ror:8 row_mask:0xf bank_mask:0xf
	s_nop 0
	v_cmp_le_u32_e32 vcc, 0x100, v45
	s_nop 1
	v_cndmask_b32_e32 v36, v36, v42, vcc
	v_cndmask_b32_e32 v46, v46, v45, vcc
	v_cndmask_b32_e32 v47, v47, v44, vcc
	v_and_b32_e32 v41, 0x7f, v36
	v_lshlrev_b32_e32 v41, v39, v41
	v_add_u32_e32 v41, v34, v41
	v_cmp_ge_u32_e32 vcc, 0x120, v46
	v_cmp_eq_u32_e64 s[0:1], 0, v39
	v_lshlrev_b32_e32 v42, v39, v200
	v_add_u32_e32 v42, -1, v42
	s_or_b64 vcc, vcc, s[0:1]
	s_andn2_b64 s[0:1], vcc, s[50:51]
	s_nor_b64 s[2:3], vcc, s[50:51]
	s_or_b64 s[50:51], s[50:51], vcc
	v_add_u32_e64 v42, v41, v42 clamp
	v_min_u32_e32 v42, v42, v35
	v_cndmask_b32_e64 v37, v37, v41, s[0:1]
	v_cndmask_b32_e64 v62, v62, v47, s[0:1]
	v_cndmask_b32_e64 v35, v35, v42, s[2:3]
	v_cndmask_b32_e64 v34, v34, v41, s[2:3]
	s_cmp_eq_u64 s[50:51], -1
	s_cbranch_scc0 .Lp2apr1_iter
	s_mov_b64 exec, s[22:23]
	v_mov_b32_e32 v61, v62
	s_nop 1
	v_add_u32_dpp v61, v61, v61 row_shr:1 row_mask:0xf bank_mask:0xf bound_ctrl:1
	s_nop 1
	v_add_u32_dpp v61, v61, v61 row_shr:2 row_mask:0xf bank_mask:0xf bound_ctrl:1
	s_nop 1
	v_add_u32_dpp v61, v61, v61 row_shr:4 row_mask:0xf bank_mask:0xf bound_ctrl:1
	s_nop 1
	v_add_u32_dpp v61, v61, v61 row_shr:8 row_mask:0xf bank_mask:0xf bound_ctrl:1
	v_sub_u32_e32 v62, v61, v62
	v_lshl_add_u32 v41, v62, 2, v59
	v_cmpx_ge_u32_e32 vcc, v0, v37
	v_add_u32_e32 v62, 1, v62
	ds_write_b32 v41, v0
	s_mov_b64 exec, s[22:23]
	v_lshl_add_u32 v41, v62, 2, v59
	v_cmpx_ge_u32_e32 vcc, v1, v37
	v_add_u32_e32 v62, 1, v62
	ds_write_b32 v41, v1
	s_mov_b64 exec, s[22:23]
	v_lshl_add_u32 v41, v62, 2, v59
	v_cmpx_ge_u32_e32 vcc, v2, v37
	v_add_u32_e32 v62, 1, v62
	ds_write_b32 v41, v2
	s_mov_b64 exec, s[22:23]
	v_lshl_add_u32 v41, v62, 2, v59
	v_cmpx_ge_u32_e32 vcc, v3, v37
	v_add_u32_e32 v62, 1, v62
	ds_write_b32 v41, v3
	s_mov_b64 exec, s[22:23]
	v_lshl_add_u32 v41, v62, 2, v59
	v_cmpx_ge_u32_e32 vcc, v4, v37
	v_add_u32_e32 v62, 1, v62
	ds_write_b32 v41, v4
	s_mov_b64 exec, s[22:23]
	v_lshl_add_u32 v41, v62, 2, v59
	v_cmpx_ge_u32_e32 vcc, v5, v37
	v_add_u32_e32 v62, 1, v62
	ds_write_b32 v41, v5
	s_mov_b64 exec, s[22:23]
	v_lshl_add_u32 v41, v62, 2, v59
	v_cmpx_ge_u32_e32 vcc, v6, v37
	v_add_u32_e32 v62, 1, v62
	ds_write_b32 v41, v6
	s_mov_b64 exec, s[22:23]
	v_lshl_add_u32 v41, v62, 2, v59
	v_cmpx_ge_u32_e32 vcc, v7, v37
	v_add_u32_e32 v62, 1, v62
	ds_write_b32 v41, v7
	s_mov_b64 exec, s[22:23]
	v_lshl_add_u32 v41, v62, 2, v59
	v_cmpx_ge_u32_e32 vcc, v8, v37
	v_add_u32_e32 v62, 1, v62
	ds_write_b32 v41, v8
	s_mov_b64 exec, s[22:23]
	v_lshl_add_u32 v41, v62, 2, v59
	v_cmpx_ge_u32_e32 vcc, v9, v37
	v_add_u32_e32 v62, 1, v62
	ds_write_b32 v41, v9
	s_mov_b64 exec, s[22:23]
	v_lshl_add_u32 v41, v62, 2, v59
	v_cmpx_ge_u32_e32 vcc, v10, v37
	v_add_u32_e32 v62, 1, v62
	ds_write_b32 v41, v10
	s_mov_b64 exec, s[22:23]
	v_lshl_add_u32 v41, v62, 2, v59
	v_cmpx_ge_u32_e32 vcc, v11, v37
	v_add_u32_e32 v62, 1, v62
	ds_write_b32 v41, v11
	s_mov_b64 exec, s[22:23]
	v_lshl_add_u32 v41, v62, 2, v59
	v_cmpx_ge_u32_e32 vcc, v12, v37
	v_add_u32_e32 v62, 1, v62
	ds_write_b32 v41, v12
	s_mov_b64 exec, s[22:23]
	v_lshl_add_u32 v41, v62, 2, v59
	v_cmpx_ge_u32_e32 vcc, v13, v37
	v_add_u32_e32 v62, 1, v62
	ds_write_b32 v41, v13
	s_mov_b64 exec, s[22:23]
	v_lshl_add_u32 v41, v62, 2, v59
	v_cmpx_ge_u32_e32 vcc, v14, v37
	v_add_u32_e32 v62, 1, v62
	ds_write_b32 v41, v14
	s_mov_b64 exec, s[22:23]
	v_lshl_add_u32 v41, v62, 2, v59
	v_cmpx_ge_u32_e32 vcc, v15, v37
	v_add_u32_e32 v62, 1, v62
	ds_write_b32 v41, v15
	s_mov_b64 exec, s[22:23]
	v_lshl_add_u32 v41, v62, 2, v59
	v_cmpx_ge_u32_e32 vcc, v16, v37
	v_add_u32_e32 v62, 1, v62
	ds_write_b32 v41, v16
	s_mov_b64 exec, s[22:23]
	v_lshl_add_u32 v41, v62, 2, v59
	v_cmpx_ge_u32_e32 vcc, v17, v37
	v_add_u32_e32 v62, 1, v62
	ds_write_b32 v41, v17
	s_mov_b64 exec, s[22:23]
	v_lshl_add_u32 v41, v62, 2, v59
	v_cmpx_ge_u32_e32 vcc, v18, v37
	v_add_u32_e32 v62, 1, v62
	ds_write_b32 v41, v18
	s_mov_b64 exec, s[22:23]
	v_lshl_add_u32 v41, v62, 2, v59
	v_cmpx_ge_u32_e32 vcc, v19, v37
	v_add_u32_e32 v62, 1, v62
	ds_write_b32 v41, v19
	s_mov_b64 exec, s[22:23]
	v_lshl_add_u32 v41, v62, 2, v59
	v_cmpx_ge_u32_e32 vcc, v20, v37
	v_add_u32_e32 v62, 1, v62
	ds_write_b32 v41, v20
	s_mov_b64 exec, s[22:23]
	v_lshl_add_u32 v41, v62, 2, v59
	v_cmpx_ge_u32_e32 vcc, v21, v37
	v_add_u32_e32 v62, 1, v62
	ds_write_b32 v41, v21
	s_mov_b64 exec, s[22:23]
	v_lshl_add_u32 v41, v62, 2, v59
	v_cmpx_ge_u32_e32 vcc, v22, v37
	v_add_u32_e32 v62, 1, v62
	ds_write_b32 v41, v22
	s_mov_b64 exec, s[22:23]
	v_lshl_add_u32 v41, v62, 2, v59
	v_cmpx_ge_u32_e32 vcc, v23, v37
	v_add_u32_e32 v62, 1, v62
	ds_write_b32 v41, v23
	s_mov_b64 exec, s[22:23]
	v_lshl_add_u32 v41, v62, 2, v59
	v_cmpx_ge_u32_e32 vcc, v24, v37
	v_add_u32_e32 v62, 1, v62
	ds_write_b32 v41, v24
	s_mov_b64 exec, s[22:23]
	v_lshl_add_u32 v41, v62, 2, v59
	v_cmpx_ge_u32_e32 vcc, v25, v37
	v_add_u32_e32 v62, 1, v62
	ds_write_b32 v41, v25
	s_mov_b64 exec, s[22:23]
	v_lshl_add_u32 v41, v62, 2, v59
	v_cmpx_ge_u32_e32 vcc, v26, v37
	v_add_u32_e32 v62, 1, v62
	ds_write_b32 v41, v26
	s_mov_b64 exec, s[22:23]
	v_lshl_add_u32 v41, v62, 2, v59
	v_cmpx_ge_u32_e32 vcc, v27, v37
	v_add_u32_e32 v62, 1, v62
	ds_write_b32 v41, v27
	s_mov_b64 exec, s[22:23]
	v_lshl_add_u32 v41, v62, 2, v59
	v_cmpx_ge_u32_e32 vcc, v28, v37
	v_add_u32_e32 v62, 1, v62
	ds_write_b32 v41, v28
	s_mov_b64 exec, s[22:23]
	v_lshl_add_u32 v41, v62, 2, v59
	v_cmpx_ge_u32_e32 vcc, v29, v37
	v_add_u32_e32 v62, 1, v62
	ds_write_b32 v41, v29
	s_mov_b64 exec, s[22:23]
	v_lshl_add_u32 v41, v62, 2, v59
	v_cmpx_ge_u32_e32 vcc, v30, v37
	v_add_u32_e32 v62, 1, v62
	ds_write_b32 v41, v30
	s_mov_b64 exec, s[22:23]
	v_lshl_add_u32 v41, v62, 2, v59
	v_cmpx_ge_u32_e32 vcc, v31, v37
	v_add_u32_e32 v62, 1, v62
	ds_write_b32 v41, v31
	s_mov_b64 exec, s[22:23]
	s_mov_b64 exec, -1
	v_and_b32_e32 v41, 0xffffe000, v37
	v_ashrrev_i32_e32 v42, 31, v41
	v_not_b32_e32 v42, v42
	v_or_b32_e32 v42, 0x80000000, v42
	v_xor_b32_e32 v63, v41, v42
	s_cmpk_lt_i32 s8, 0x121
	s_cbranch_scc1 .Lp2apr1_o0
	v_readlane_b32 s0, v63, 0
	v_readlane_b32 s74, v37, 0
	v_readlane_b32 s8, v61, 15
	v_mov_b32_e32 v233, s0
